# pass C rotation: next unit's 15 staging loads issued after this unit's staging barrier (addresses + per-buffer unit stride), next unit skips its load block
# speedup vs baseline: 1.0089x; 1.0041x over previous
; #define LAS __attribute__((address_space(3)))
; __device__ __forceinline__ void gla_passC(LAS unsigned char* lds, int uidx, const bf16_t* PR, const bf16_t* SUB, const bf16_t* QT, const bf16_t* AM, const float* gn  ,
;                                           bf16_t* Y, int tid, int wid, int lane) {
;     const int b = uidx >> 7, c = (uidx >> 2) & 31, h = uidx & 3; const int tok0 = b * SEQ + c * 64; const int bh = b * 4 + h;
;     LAS bf16_t* Qs = (LAS bf16_t*)lds;
;     LAS bf16_t* As = (LAS bf16_t*)(lds + 17408);
;     LAS bf16_t* Vn = (LAS bf16_t*)(lds + 26624);
;     LAS bf16_t* Sn = (LAS bf16_t*)(lds + 61440);
;     LAS float* Of = (LAS float*)(lds + 61440);
;     const int r = lane & 15, q = lane >> 4;
;     u32x4 ogr[4];
;     { const bf16_t* gp0 = PR + (size_t)(tok0 + (tid >> 3)) * PRW + 3072 + h * DV + (tid & 7) * 32;
; #pragma unroll
;       for (int j = 0; j < 4; ++j) ogr[j] = *(const u32x4*)(gp0 + 8 * j); }
;     { const bf16_t* sp = SUB + ((size_t)bh * NCH + c) * (DK * DV);
; #pragma unroll
;       for (int i = 0; i < 8; ++i) { const int id = tid + 512 * i, k = id >> 5, cc = id & 31; *(LAS u32x4*)(Sn + k * 272 + cc * 8) = *(const u32x4*)(sp + k * DV + cc * 8); } }
; #pragma unroll
;     for (int i = 0; i < 2; ++i) { const int id = tid + 512 * i, row = id >> 4, cc = id & 15; *(LAS u32x4*)(Qs + row * 136 + cc * 8) = *(const u32x4*)(QT + (size_t)(tok0 + row) * QKD + h * DK + cc * 8); }
;     { const int row = tid >> 3, cc = tid & 7; *(LAS u32x4*)(As + row * 72 + cc * 8) = *(const u32x4*)(AM + (size_t)uidx * 4096 + row * 64 + cc * 8); }
;     stage_v(Vn, PR, tok0, h, tid);
.LBB0_485:
	s_or_b64 exec, exec, s[2:3]
	v_readlane_b32 s4, v245, 19
	s_mov_b64 s[2:3], s[90:91]
	s_waitcnt lgkmcnt(0)
	v_mov_b32_e32 v0, v210
	v_readlane_b32 s5, v245, 20
	s_barrier
	s_and_b64 vcc, exec, s[4:5]
	v_readfirstlane_b32 s22, v0
	v_readlane_b32 s93, v246, 5
	s_cbranch_vccz .LBB0_488
	s_load_dwordx2 s[4:5], s[2:3], 0x50
	v_readlane_b32 s6, v244, 32
	s_load_dwordx2 s[2:3], s[2:3], 0x98
	v_readlane_b32 s7, v244, 33
	s_lshl_b32 s10, s6, 10
	s_lshl_b64 s[6:7], s[10:11], 2
	v_add_u32_e32 v6, 0x400, v0
	s_waitcnt lgkmcnt(0)
	s_add_u32 s6, s4, s6
	v_ashrrev_i32_e32 v81, 5, v6
	v_add_u32_e32 v6, 0x600, v0
	s_addc_u32 s7, s5, s7
	v_ashrrev_i32_e32 v82, 5, v6
	v_add_u32_e32 v6, 0x800, v0
	s_add_u32 s4, s2, 0x12900000
	s_movk_i32 s23, 0x220
	v_add_u32_e32 v9, 0x200, v0
	v_ashrrev_i32_e32 v6, 5, v6
	s_addc_u32 s5, s3, 0
	v_lshlrev_b32_e32 v56, 8, v6
	v_mul_lo_u32 v13, v6, s23
	v_add_u32_e32 v6, 0xa00, v0
	v_ashrrev_i32_e32 v83, 4, v0
	s_movk_i32 s10, 0x110
	v_ashrrev_i32_e32 v84, 4, v9
	s_add_u32 s8, s2, 0x1ad84000
	v_ashrrev_i32_e32 v78, 3, v0
	v_ashrrev_i32_e32 v80, 5, v9
	v_ashrrev_i32_e32 v6, 5, v6
	v_mul_lo_u32 v18, v83, s10
	v_mul_lo_u32 v9, v84, s10
	s_movk_i32 s10, 0x90
	s_addc_u32 s9, s3, 0
	v_lshlrev_b32_e32 v58, 8, v6
	v_mul_lo_u32 v14, v6, s23
	v_add_u32_e32 v6, 0xc00, v0
	v_mul_lo_u32 v19, v78, s10
	s_and_b32 s10, s22, 0xffffffc0
	v_and_b32_e32 v1, 15, v0
	v_ashrrev_i32_e32 v6, 5, v6
	s_add_i32 s10, s10, 0
	v_and_b32_e32 v3, 7, v0
	v_lshlrev_b32_e32 v60, 8, v6
	v_mul_lo_u32 v15, v6, s23
	v_add_u32_e32 v6, 0xe00, v0
	v_lshl_add_u32 v21, v1, 1, s10
	s_lshl_b32 s10, s22, 1
	v_ashrrev_i32_e32 v6, 5, v6
	v_lshlrev_b32_e32 v20, 4, v3
	s_and_b32 s10, s10, 0xffffff80
	v_lshlrev_b32_e32 v4, 3, v0
	v_ashrrev_i32_e32 v79, 5, v0
	v_lshlrev_b32_e32 v62, 8, v6
	v_mul_lo_u32 v16, v6, s23
	v_lshlrev_b32_e32 v6, 4, v0
	v_add3_u32 v85, 0, v19, v20
	v_lshrrev_b32_e32 v19, 1, v0
	v_and_b32_e32 v0, 48, v0
	s_add_i32 s10, s10, 0
	v_and_b32_e32 v168, 0xf0, v6
	v_add_u32_e32 v26, s10, v0
	s_movk_i32 s10, 0x410
	v_lshl_add_u64 v[6:7], s[2:3], 0, v[168:169]
	v_add_u32_e32 v17, 0, v168
	v_mul_u32_u24_e32 v23, 0x110, v1
	v_add_u32_e32 v24, 0, v0
	v_mul_u32_u24_e32 v25, 0x90, v1
	v_mul_u32_u24_e32 v27, 0x410, v1
	v_mad_u32_u24 v28, v1, s10, v221
	v_mad_u32_u24 v29, v1, s10, v222
	v_mad_u32_u24 v30, v1, s10, v223
	v_mul_lo_u32 v0, v78, s10
	v_lshlrev_b32_e32 v168, 7, v3
	v_and_b32_e32 v1, 64, v211
	v_add3_u32 v88, 0, v0, v168
	v_xor_b32_e32 v0, 1, v211
	v_add_u32_e32 v1, 64, v1
	v_cmp_lt_i32_e32 vcc, v0, v1
	s_mov_b64 s[24:25], 0x1edc4000
	v_lshl_add_u64 v[64:65], v[6:7], 0, s[24:25]
	v_cndmask_b32_e32 v0, v211, v0, vcc
	v_lshlrev_b32_e32 v89, 2, v0
	v_xor_b32_e32 v0, 2, v211
	v_cmp_lt_i32_e32 vcc, v0, v1
	v_lshlrev_b32_e32 v6, 6, v78
	v_ashrrev_i32_e32 v7, 31, v6
	v_cndmask_b32_e32 v0, v211, v0, vcc
	v_lshlrev_b32_e32 v90, 2, v0
	v_xor_b32_e32 v0, 4, v211
	v_cmp_lt_i32_e32 vcc, v0, v1
	v_lshl_add_u64 v[66:67], s[6:7], 0, v[168:169]
	v_readlane_b32 s6, v245, 54
	v_cndmask_b32_e32 v0, v211, v0, vcc
	v_and_b32_e32 v4, 0xf8, v4
	v_and_b32_e32 v19, 24, v19
	v_lshlrev_b32_e32 v91, 2, v0
	s_add_u32 s6, s2, s6
	v_readlane_b32 s7, v245, 55
	v_lshlrev_b64 v[0:1], 1, v[6:7]
	v_lshlrev_b32_e32 v2, 5, v3
	v_lshl_add_u32 v5, v4, 1, 0
	v_lshlrev_b32_e32 v48, 8, v79
	v_mul_lo_u32 v8, v79, s23
	v_lshlrev_b32_e32 v50, 8, v80
	v_mul_lo_u32 v10, v80, s23
	v_lshlrev_b32_e32 v52, 8, v81
	v_mul_lo_u32 v11, v81, s23
	v_lshlrev_b32_e32 v54, 8, v82
	v_mul_lo_u32 v12, v82, s23
	v_lshl_add_u32 v22, v19, 1, 0
	v_mad_u32_u24 v86, v19, s23, v21
	v_mad_u32_u24 v19, v19, s23, v220
	s_addc_u32 s7, s3, s7
	v_or_b32_e32 v0, v0, v20
	v_ashrrev_i32_e32 v49, 31, v48
	v_ashrrev_i32_e32 v51, 31, v50
	v_ashrrev_i32_e32 v53, 31, v52
	v_ashrrev_i32_e32 v55, 31, v54
	v_ashrrev_i32_e32 v57, 31, v56
	v_ashrrev_i32_e32 v59, 31, v58
	v_ashrrev_i32_e32 v61, 31, v60
	v_ashrrev_i32_e32 v63, 31, v62
	v_add_u32_e32 v87, 0xf000, v86
	v_lshl_add_u64 v[68:69], s[6:7], 0, v[0:1]
	v_lshlrev_b32_e32 v168, 1, v2
	v_lshlrev_b32_e32 v70, 1, v4
	v_add_u32_e32 v92, v5, v8
	v_add_u32_e32 v93, v5, v10
	v_add_u32_e32 v94, v5, v11
	v_add_u32_e32 v95, v5, v12
	v_add_u32_e32 v96, v5, v13
	v_add_u32_e32 v97, v5, v14
	v_add_u32_e32 v98, v5, v15
	v_add_u32_e32 v99, v5, v16
	v_add_u32_e32 v100, v17, v18
	v_add_u32_e32 v101, v17, v9
	v_add_u32_e32 v102, v22, v23
	v_add_u32_e32 v103, v21, v19
	v_add_u32_e32 v104, v24, v25
	v_add_u32_e32 v105, v26, v27
	v_add_u32_e32 v106, v26, v28
	v_add_u32_e32 v107, v26, v29
	v_add_u32_e32 v108, v26, v30
	s_mov_b32 s6, s92
	s_mov_b32 s60, 0
; #define LAS __attribute__((address_space(3)))
; __device__ __forceinline__ void gla_passC(LAS unsigned char* lds, int uidx, const bf16_t* PR, const bf16_t* SUB, const bf16_t* QT, const bf16_t* AM, const float* gn  ,
;                                           bf16_t* Y, int tid, int wid, int lane) {
;     ...
;     u32x4 ogr[4];
;     { const bf16_t* gp0 = PR + (size_t)(tok0 + (tid >> 3)) * PRW + 3072 + h * DV + (tid & 7) * 32;
; #pragma unroll
;       for (int j = 0; j < 4; ++j) ogr[j] = *(const u32x4*)(gp0 + 8 * j); }
;     { const bf16_t* sp = SUB + ((size_t)bh * NCH + c) * (DK * DV);
; #pragma unroll
;       for (int i = 0; i < 8; ++i) { const int id = tid + 512 * i, k = id >> 5, cc = id & 31; *(LAS u32x4*)(Sn + k * 272 + cc * 8) = *(const u32x4*)(sp + k * DV + cc * 8); } }
; #pragma unroll
;     for (int i = 0; i < 2; ++i) { const int id = tid + 512 * i, row = id >> 4, cc = id & 15; *(LAS u32x4*)(Qs + row * 136 + cc * 8) = *(const u32x4*)(QT + (size_t)(tok0 + row) * QKD + h * DK + cc * 8); }
;     { const int row = tid >> 3, cc = tid & 7; *(LAS u32x4*)(As + row * 72 + cc * 8) = *(const u32x4*)(AM + (size_t)uidx * 4096 + row * 64 + cc * 8); }
;     stage_v(Vn, PR, tok0, h, tid);
.LBB0_487:
	s_ashr_i32 s10, s6, 7
	s_bfe_u32 s25, s6, 0x50002
	s_lshl_b32 s22, s10, 11
	s_lshl_b32 s23, s25, 6
	s_and_b32 s7, s6, 3
	s_or_b32 s24, s23, s22
	s_lshl_b32 s10, s10, 2
	s_or_b32 s26, s10, s7
	v_add_u32_e32 v74, s24, v78
	v_ashrrev_i32_e32 v75, 31, v74
	s_ashr_i32 s27, s26, 31
	v_lshlrev_b64 v[0:1], 13, v[74:75]
	s_lshl_b32 s10, s7, 8
	s_lshl_b32 s22, s7, 9
	s_lshl_b64 s[26:27], s[26:27], 21
	v_lshl_add_u64 v[0:1], s[4:5], 0, v[0:1]
	s_mov_b32 s23, s11
	s_add_u32 s26, s8, s26
	v_lshl_add_u64 v[0:1], v[0:1], 0, s[22:23]
	s_addc_u32 s27, s9, s27
	s_lshl_b32 s25, s25, 16
	v_lshl_add_u64 v[0:1], v[0:1], 0, v[168:169]
	s_mov_b64 s[28:29], 0x1800
	s_add_u32 s26, s26, s25
	v_lshl_add_u64 v[8:9], v[0:1], 0, s[28:29]
	v_add_co_u32_e32 v0, vcc, s15, v0
	s_addc_u32 s27, s27, 0
	v_mov_b32_e32 v71, v169
	v_addc_co_u32_e32 v1, vcc, 0, v1, vcc
	v_lshl_add_u64 v[12:13], s[26:27], 0, v[70:71]
	global_load_dwordx4 v[36:39], v[0:1], off offset:2048
	s_nop 0
	global_load_dwordx4 v[0:3], v[8:9], off offset:48
	global_load_dwordx4 v[4:7], v[8:9], off offset:32
	global_load_dwordx4 v[20:23], v[8:9], off offset:16
	v_lshl_add_u64 v[198:199], v[48:49], 1, v[12:13]
	v_lshlrev_b64 v[74:75], 12, v[74:75]
	v_lshl_add_u64 v[74:75], s[2:3], 0, v[74:75]
	v_lshl_add_u64 v[74:75], v[74:75], 0, s[22:23]
	s_add_i32 s6, s6, s82
	v_lshl_add_u64 v[200:201], v[50:51], 1, v[12:13]
	v_lshl_add_u64 v[202:203], v[52:53], 1, v[12:13]
	v_lshl_add_u64 v[204:205], v[54:55], 1, v[12:13]
	v_lshl_add_u64 v[206:207], v[56:57], 1, v[12:13]
	v_lshl_add_u64 v[208:209], v[58:59], 1, v[12:13]
	v_lshl_add_u64 v[228:229], v[60:61], 1, v[12:13]
	v_lshl_add_u64 v[230:231], v[62:63], 1, v[12:13]
	v_lshl_add_u64 v[12:13], v[64:65], 0, s[10:11]
	s_lshl_b32 s10, s7, 10
	s_mov_b32 s7, 0x18c84000
	s_cmpk_gt_i32 s6, 0x1ff
	v_add_u32_e32 v232, s24, v83
	v_ashrrev_i32_e32 v233, 31, v232
	v_lshlrev_b64 v[232:233], 10, v[232:233]
	v_lshl_add_u64 v[232:233], v[12:13], 0, v[232:233]
	v_add_u32_e32 v234, s24, v84
	v_ashrrev_i32_e32 v235, 31, v234
	v_lshlrev_b64 v[234:235], 10, v[234:235]
	v_lshl_add_u64 v[234:235], v[12:13], 0, v[234:235]
	v_add_u32_e32 v236, s24, v79
	v_ashrrev_i32_e32 v237, 31, v236
	v_lshlrev_b64 v[236:237], 13, v[236:237]
	v_lshl_add_u64 v[236:237], s[4:5], 0, v[236:237]
	v_lshl_add_u64 v[236:237], v[236:237], 0, s[22:23]
	v_lshl_add_u64 v[236:237], v[236:237], 0, v[70:71]
	v_add_co_u32_e32 v236, vcc, s15, v236
	s_nop 1
	v_addc_co_u32_e32 v237, vcc, 0, v237, vcc
	v_add_u32_e32 v238, s24, v80
	v_ashrrev_i32_e32 v239, 31, v238
	v_lshlrev_b64 v[238:239], 13, v[238:239]
	v_lshl_add_u64 v[238:239], s[4:5], 0, v[238:239]
	v_lshl_add_u64 v[238:239], v[238:239], 0, s[22:23]
	v_lshl_add_u64 v[238:239], v[238:239], 0, v[70:71]
	v_add_co_u32_e32 v238, vcc, s15, v238
	s_nop 1
	v_addc_co_u32_e32 v239, vcc, 0, v239, vcc
	v_add_u32_e32 v240, s24, v81
	v_ashrrev_i32_e32 v241, 31, v240
	v_lshlrev_b64 v[240:241], 13, v[240:241]
	v_lshl_add_u64 v[240:241], s[4:5], 0, v[240:241]
	v_lshl_add_u64 v[240:241], v[240:241], 0, s[22:23]
	v_lshl_add_u64 v[240:241], v[240:241], 0, v[70:71]
	v_add_co_u32_e32 v240, vcc, s15, v240
	s_nop 1
	v_addc_co_u32_e32 v241, vcc, 0, v241, vcc
	v_add_u32_e32 v242, s24, v82
	v_ashrrev_i32_e32 v243, 31, v242
	v_lshlrev_b64 v[242:243], 13, v[242:243]
	v_lshl_add_u64 v[242:243], s[4:5], 0, v[242:243]
	v_lshl_add_u64 v[242:243], v[242:243], 0, s[22:23]
	v_lshl_add_u64 v[242:243], v[242:243], 0, v[70:71]
	v_add_co_u32_e32 v242, vcc, s15, v242
	s_mov_b64 s[22:23], 0x18c84800
	s_nop 0
	v_addc_co_u32_e32 v243, vcc, 0, v243, vcc
	s_cmp_lg_u32 s60, 0
	s_mov_b32 s60, 0
	s_cbranch_scc1 .Lpc_have
	global_load_dwordx4 v[128:131], v[198:199], off
	global_load_dwordx4 v[132:135], v[200:201], off
	global_load_dwordx4 v[136:139], v[202:203], off
	global_load_dwordx4 v[140:143], v[204:205], off
	global_load_dwordx4 v[144:147], v[206:207], off
	global_load_dwordx4 v[148:151], v[208:209], off
	global_load_dwordx4 v[152:155], v[228:229], off
	global_load_dwordx4 v[156:159], v[230:231], off
	global_load_dwordx4 v[160:163], v[232:233], off
	global_load_dwordx4 v[164:167], v[234:235], off
	global_load_dwordx4 v[178:181], v[68:69], off
	global_load_dwordx4 v[182:185], v[236:237], off
	global_load_dwordx4 v[186:189], v[238:239], off
	global_load_dwordx4 v[190:193], v[240:241], off
	global_load_dwordx4 v[194:197], v[242:243], off
; #define LAS __attribute__((address_space(3)))
; #define MFMA16(x, y, c) __builtin_amdgcn_mfma_f32_16x16x32_bf16((x), (y), (c), 0, 0, 0)
; __device__ __forceinline__ void gla_passC(LAS unsigned char* lds, int uidx, const bf16_t* PR, const bf16_t* SUB, const bf16_t* QT, const bf16_t* AM, const float* gn  ,
;                                           bf16_t* Y, int tid, int wid, int lane) {
;     ...
;     { const bf16_t* sp = SUB + ((size_t)bh * NCH + c) * (DK * DV);
; #pragma unroll
;       for (int i = 0; i < 8; ++i) { const int id = tid + 512 * i, k = id >> 5, cc = id & 31; *(LAS u32x4*)(Sn + k * 272 + cc * 8) = *(const u32x4*)(sp + k * DV + cc * 8); } }
; #pragma unroll
;     for (int i = 0; i < 2; ++i) { const int id = tid + 512 * i, row = id >> 4, cc = id & 15; *(LAS u32x4*)(Qs + row * 136 + cc * 8) = *(const u32x4*)(QT + (size_t)(tok0 + row) * QKD + h * DK + cc * 8); }
;     { const int row = tid >> 3, cc = tid & 7; *(LAS u32x4*)(As + row * 72 + cc * 8) = *(const u32x4*)(AM + (size_t)uidx * 4096 + row * 64 + cc * 8); }
;     stage_v(Vn, PR, tok0, h, tid);
;     __syncthreads();
;     f32x4 acc[2][4];
; #pragma unroll
;     for (int a = 0; a < 2; ++a)
; #pragma unroll
;         for (int it = 0; it < 4; ++it) acc[a][it] = (f32x4){0.f, 0.f, 0.f, 0.f};
; #pragma unroll
;     for (int ks = 0; ks < 4; ++ks) { bf16x8 x[2];
; #pragma unroll
;         for (int a = 0; a < 2; ++a) x[a] = tr_frag<272>(Sn, 2 * wid + a, ks, lane);
; #pragma unroll
;         for (int it = 0; it < 4; ++it) { const bf16x8 y = *(const LAS bf16x8*)(Qs + (16 * it + r) * 136 + 32 * ks + 8 * q);
; #pragma unroll
;             for (int a = 0; a < 2; ++a) acc[a][it] = MFMA16(x[a], y, acc[a][it]); } }
.Lpc_have:
	v_lshl_add_u64 v[68:69], v[68:69], 0, s[34:35]
	s_waitcnt vmcnt(14)
	ds_write_b128 v92, v[128:131] offset:61440
	s_waitcnt vmcnt(13)
	ds_write_b128 v93, v[132:135] offset:61440
	s_waitcnt vmcnt(12)
	ds_write_b128 v94, v[136:139] offset:61440
	s_waitcnt vmcnt(11)
	ds_write_b128 v95, v[140:143] offset:61440
	s_waitcnt vmcnt(10)
	ds_write_b128 v96, v[144:147] offset:61440
	s_waitcnt vmcnt(9)
	ds_write_b128 v97, v[148:151] offset:61440
	s_waitcnt vmcnt(8)
	ds_write_b128 v98, v[152:155] offset:61440
	s_waitcnt vmcnt(7)
	ds_write_b128 v99, v[156:159] offset:61440
	s_waitcnt vmcnt(6)
	ds_write_b128 v100, v[160:163]
	s_waitcnt vmcnt(5)
	ds_write_b128 v101, v[164:167]
	s_waitcnt vmcnt(4)
	ds_write_b128 v85, v[178:181] offset:17408
	s_waitcnt vmcnt(3)
	ds_write_b128 v92, v[182:185] offset:26624
	s_waitcnt vmcnt(2)
	ds_write_b128 v93, v[186:189] offset:26624
	s_waitcnt vmcnt(1)
	ds_write_b128 v94, v[190:193] offset:26624
	s_waitcnt vmcnt(0)
	ds_write_b128 v95, v[194:197] offset:26624
	s_waitcnt lgkmcnt(0)
	s_barrier
	s_cmpk_gt_i32 s6, 0x1ff
	s_cbranch_scc1 .Lpc_nopf
	s_and_b32 s62, s82, 0x7f
	s_cmp_eq_u32 s62, 0
	s_cbranch_scc0 .Lpc_nopf
	s_lshr_b32 s62, s82, 7
	s_lshl_b32 s64, s62, 23
	s_lshl_b32 s65, s62, 24
	s_lshl_b32 s66, s62, 21
	v_add_co_u32_e32 v198, vcc, s64, v198
	s_nop 0
	v_addc_co_u32_e32 v199, vcc, 0, v199, vcc
	global_load_dwordx4 v[128:131], v[198:199], off
	v_add_co_u32_e32 v200, vcc, s64, v200
	s_nop 0
	v_addc_co_u32_e32 v201, vcc, 0, v201, vcc
	global_load_dwordx4 v[132:135], v[200:201], off
	v_add_co_u32_e32 v202, vcc, s64, v202
	s_nop 0
	v_addc_co_u32_e32 v203, vcc, 0, v203, vcc
	global_load_dwordx4 v[136:139], v[202:203], off
	v_add_co_u32_e32 v204, vcc, s64, v204
	s_nop 0
	v_addc_co_u32_e32 v205, vcc, 0, v205, vcc
	global_load_dwordx4 v[140:143], v[204:205], off
	v_add_co_u32_e32 v206, vcc, s64, v206
	s_nop 0
	v_addc_co_u32_e32 v207, vcc, 0, v207, vcc
	global_load_dwordx4 v[144:147], v[206:207], off
	v_add_co_u32_e32 v208, vcc, s64, v208
	s_nop 0
	v_addc_co_u32_e32 v209, vcc, 0, v209, vcc
	global_load_dwordx4 v[148:151], v[208:209], off
	v_add_co_u32_e32 v228, vcc, s64, v228
	s_nop 0
	v_addc_co_u32_e32 v229, vcc, 0, v229, vcc
	global_load_dwordx4 v[152:155], v[228:229], off
	v_add_co_u32_e32 v230, vcc, s64, v230
	s_nop 0
	v_addc_co_u32_e32 v231, vcc, 0, v231, vcc
	global_load_dwordx4 v[156:159], v[230:231], off
	v_add_co_u32_e32 v232, vcc, s66, v232
	s_nop 0
	v_addc_co_u32_e32 v233, vcc, 0, v233, vcc
	global_load_dwordx4 v[160:163], v[232:233], off
	v_add_co_u32_e32 v234, vcc, s66, v234
	s_nop 0
	v_addc_co_u32_e32 v235, vcc, 0, v235, vcc
	global_load_dwordx4 v[164:167], v[234:235], off
	global_load_dwordx4 v[178:181], v[68:69], off
	v_add_co_u32_e32 v236, vcc, s65, v236
	s_nop 0
	v_addc_co_u32_e32 v237, vcc, 0, v237, vcc
	global_load_dwordx4 v[182:185], v[236:237], off
	v_add_co_u32_e32 v238, vcc, s65, v238
	s_nop 0
	v_addc_co_u32_e32 v239, vcc, 0, v239, vcc
	global_load_dwordx4 v[186:189], v[238:239], off
	v_add_co_u32_e32 v240, vcc, s65, v240
	s_nop 0
	v_addc_co_u32_e32 v241, vcc, 0, v241, vcc
	global_load_dwordx4 v[190:193], v[240:241], off
	v_add_co_u32_e32 v242, vcc, s65, v242
	s_nop 0
	v_addc_co_u32_e32 v243, vcc, 0, v243, vcc
	global_load_dwordx4 v[194:197], v[242:243], off
	s_mov_b32 s60, 1
.Lpc_nopf:
	ds_read_u16 v8, v86 offset:61440
	ds_read_u16 v12, v86 offset:61984
	ds_read_u16 v9, v86 offset:62528
	ds_read_u16 v13, v86 offset:63072
	ds_read_u16 v10, v86 offset:63616
	ds_read_u16 v14, v86 offset:64160
	ds_read_u16 v11, v86 offset:64704
	ds_read_u16 v15, v86 offset:65248
	ds_read_u16 v24, v86 offset:61472
	ds_read_u16 v28, v86 offset:62016
	ds_read_u16 v25, v86 offset:62560
	ds_read_u16 v29, v86 offset:63104
	ds_read_u16 v26, v86 offset:63648
	ds_read_u16 v30, v86 offset:64192
	ds_read_u16 v27, v86 offset:64736
	ds_read_u16 v31, v86 offset:65280
	s_waitcnt lgkmcnt(8)
	v_perm_b32 v11, v15, v11, s13
	v_perm_b32 v10, v14, v10, s13
	v_perm_b32 v9, v13, v9, s13
	v_perm_b32 v8, v12, v8, s13
	ds_read_b128 v[12:15], v102
	s_waitcnt lgkmcnt(1)
	v_perm_b32 v27, v31, v27, s13
	v_perm_b32 v26, v30, v26, s13
	v_perm_b32 v25, v29, v25, s13
	v_perm_b32 v24, v28, v24, s13
	ds_read_b128 v[28:31], v102 offset:4352
	ds_read_b128 v[40:43], v102 offset:8704
	ds_read_b128 v[110:113], v102 offset:13056
	s_waitcnt lgkmcnt(3)
	v_mfma_f32_16x16x32_bf16 v[16:19], v[8:11], v[12:15], 0
	v_mfma_f32_16x16x32_bf16 v[12:15], v[24:27], v[12:15], 0
	s_waitcnt lgkmcnt(2)
	v_mfma_f32_16x16x32_bf16 v[32:35], v[8:11], v[28:31], 0
	v_mfma_f32_16x16x32_bf16 v[28:31], v[24:27], v[28:31], 0
	s_waitcnt lgkmcnt(1)
	v_mfma_f32_16x16x32_bf16 v[44:47], v[8:11], v[40:43], 0
	v_mfma_f32_16x16x32_bf16 v[40:43], v[24:27], v[40:43], 0
	s_waitcnt lgkmcnt(0)
	v_mfma_f32_16x16x32_bf16 v[8:11], v[8:11], v[110:113], 0
	v_mfma_f32_16x16x32_bf16 v[24:27], v[24:27], v[110:113], 0
	ds_read_u16 v71, v103 offset:61984
	ds_read_u16 v72, v103 offset:62528
	ds_read_u16 v73, v103 offset:63072
	ds_read_u16 v76, v103 offset:63616
	ds_read_u16 v77, v103 offset:64160
	ds_read_u16 v109, v103 offset:64704
	ds_read_u16 v110, v103 offset:65248
	ds_read_u16 v114, v103 offset:61440
	ds_read_u16 v118, v103 offset:61472
	ds_read_u16 v122, v103 offset:62016
	ds_read_u16 v119, v103 offset:62560
	ds_read_u16 v123, v103 offset:63104
	ds_read_u16 v120, v103 offset:63648
	ds_read_u16 v124, v103 offset:64192
	ds_read_u16 v121, v103 offset:64736
	ds_read_u16 v125, v103 offset:65280
	s_waitcnt lgkmcnt(9)
	v_perm_b32 v113, v110, v109, s13
	v_perm_b32 v112, v77, v76, s13
	v_perm_b32 v111, v73, v72, s13
	s_waitcnt lgkmcnt(8)
	v_perm_b32 v110, v71, v114, s13
	ds_read_b128 v[114:117], v102 offset:64
	s_waitcnt lgkmcnt(1)
; #define LAS __attribute__((address_space(3)))
; #define MFMA16(x, y, c) __builtin_amdgcn_mfma_f32_16x16x32_bf16((x), (y), (c), 0, 0, 0)
; __device__ __forceinline__ void gla_passC(LAS unsigned char* lds, int uidx, const bf16_t* PR, const bf16_t* SUB, const bf16_t* QT, const bf16_t* AM, const float* gn  ,
;                                           bf16_t* Y, int tid, int wid, int lane) {
;     ...
;     for (int ks = 0; ks < 4; ++ks) { bf16x8 x[2];
; #pragma unroll
;         for (int a = 0; a < 2; ++a) x[a] = tr_frag<272>(Sn, 2 * wid + a, ks, lane);
; #pragma unroll
;         for (int it = 0; it < 4; ++it) { const bf16x8 y = *(const LAS bf16x8*)(Qs + (16 * it + r) * 136 + 32 * ks + 8 * q);
; #pragma unroll
;             for (int a = 0; a < 2; ++a) acc[a][it] = MFMA16(x[a], y, acc[a][it]); } }
; #pragma unroll
;     for (int ks = 0; ks < 2; ++ks) { bf16x8 x[2];
; #pragma unroll
;         for (int a = 0; a < 2; ++a) x[a] = tr_frag<272>(Vn, 2 * wid + a, ks, lane);
; #pragma unroll
;         for (int it = 0; it < 4; ++it) { const bf16x8 y = *(const LAS bf16x8*)(As + (16 * it + r) * 72 + 32 * ks + 8 * q);
; #pragma unroll
;             for (int a = 0; a < 2; ++a) acc[a][it] = MFMA16(x[a], y, acc[a][it]); } }
	v_perm_b32 v121, v125, v121, s13
	v_perm_b32 v120, v124, v120, s13
	v_perm_b32 v119, v123, v119, s13
	v_perm_b32 v118, v122, v118, s13
	s_waitcnt lgkmcnt(0)
	v_mfma_f32_16x16x32_bf16 v[16:19], v[110:113], v[114:117], v[16:19]
	v_mfma_f32_16x16x32_bf16 v[12:15], v[118:121], v[114:117], v[12:15]
	ds_read_b128 v[114:117], v102 offset:4416
	s_waitcnt lgkmcnt(0)
	v_mfma_f32_16x16x32_bf16 v[32:35], v[110:113], v[114:117], v[32:35]
	v_mfma_f32_16x16x32_bf16 v[28:31], v[118:121], v[114:117], v[28:31]
	ds_read_b128 v[114:117], v102 offset:8768
	s_waitcnt lgkmcnt(0)
	v_mfma_f32_16x16x32_bf16 v[44:47], v[110:113], v[114:117], v[44:47]
	v_mfma_f32_16x16x32_bf16 v[40:43], v[118:121], v[114:117], v[40:43]
	ds_read_b128 v[114:117], v102 offset:13120
	s_waitcnt lgkmcnt(0)
	v_mfma_f32_16x16x32_bf16 v[8:11], v[110:113], v[114:117], v[8:11]
	v_mfma_f32_16x16x32_bf16 v[24:27], v[118:121], v[114:117], v[24:27]
	ds_read_u16 v71, v87 offset:35360
	ds_read_u16 v72, v87 offset:35904
	ds_read_u16 v73, v87 offset:36448
	ds_read_u16 v76, v87 offset:36992
	ds_read_u16 v77, v87 offset:37536
	ds_read_u16 v109, v87 offset:38080
	ds_read_u16 v110, v87 offset:38624
	ds_read_u16 v114, v87 offset:34816
	ds_read_u16 v118, v87 offset:34848
	ds_read_u16 v122, v87 offset:35392
	ds_read_u16 v119, v87 offset:35936
	ds_read_u16 v123, v87 offset:36480
	ds_read_u16 v120, v87 offset:37024
	ds_read_u16 v124, v87 offset:37568
	ds_read_u16 v121, v87 offset:38112
	ds_read_u16 v125, v87 offset:38656
	s_waitcnt lgkmcnt(9)
	v_perm_b32 v113, v110, v109, s13
	v_perm_b32 v112, v77, v76, s13
	v_perm_b32 v111, v73, v72, s13
	s_waitcnt lgkmcnt(8)
	v_perm_b32 v110, v71, v114, s13
	ds_read_b128 v[114:117], v102 offset:128
	s_waitcnt lgkmcnt(1)
	v_perm_b32 v121, v125, v121, s13
	v_perm_b32 v120, v124, v120, s13
	v_perm_b32 v119, v123, v119, s13
	v_perm_b32 v118, v122, v118, s13
	s_waitcnt lgkmcnt(0)
	v_mfma_f32_16x16x32_bf16 v[16:19], v[110:113], v[114:117], v[16:19]
	v_mfma_f32_16x16x32_bf16 v[12:15], v[118:121], v[114:117], v[12:15]
	ds_read_b128 v[114:117], v102 offset:4480
	s_waitcnt lgkmcnt(0)
	v_mfma_f32_16x16x32_bf16 v[32:35], v[110:113], v[114:117], v[32:35]
	v_mfma_f32_16x16x32_bf16 v[28:31], v[118:121], v[114:117], v[28:31]
	ds_read_b128 v[114:117], v102 offset:8832
	s_waitcnt lgkmcnt(0)
	v_mfma_f32_16x16x32_bf16 v[44:47], v[110:113], v[114:117], v[44:47]
	v_mfma_f32_16x16x32_bf16 v[40:43], v[118:121], v[114:117], v[40:43]
	ds_read_b128 v[114:117], v102 offset:13184
	s_waitcnt lgkmcnt(0)
	v_mfma_f32_16x16x32_bf16 v[8:11], v[110:113], v[114:117], v[8:11]
	v_mfma_f32_16x16x32_bf16 v[24:27], v[118:121], v[114:117], v[24:27]
	ds_read_u16 v71, v87 offset:52224
	ds_read_u16 v72, v87 offset:52768
	ds_read_u16 v73, v87 offset:53312
	ds_read_u16 v76, v87 offset:53856
	ds_read_u16 v77, v87 offset:54400
	ds_read_u16 v109, v87 offset:54944
	ds_read_u16 v110, v87 offset:55488
	ds_read_u16 v111, v87 offset:56032
	ds_read_u16 v118, v87 offset:52256
	ds_read_u16 v122, v87 offset:52800
	ds_read_u16 v119, v87 offset:53344
	ds_read_u16 v123, v87 offset:53888
	ds_read_u16 v120, v87 offset:54432
	ds_read_u16 v124, v87 offset:54976
	ds_read_u16 v121, v87 offset:55520
	ds_read_u16 v125, v87 offset:56064
	s_waitcnt lgkmcnt(8)
	v_perm_b32 v113, v111, v110, s13
	v_perm_b32 v112, v109, v77, s13
	v_perm_b32 v111, v76, v73, s13
	v_perm_b32 v110, v72, v71, s13
	ds_read_b128 v[114:117], v102 offset:192
	s_waitcnt lgkmcnt(1)
	v_perm_b32 v121, v125, v121, s13
	v_perm_b32 v120, v124, v120, s13
	v_perm_b32 v119, v123, v119, s13
	v_perm_b32 v118, v122, v118, s13
	s_waitcnt lgkmcnt(0)
	v_mfma_f32_16x16x32_bf16 v[16:19], v[110:113], v[114:117], v[16:19]
	v_mfma_f32_16x16x32_bf16 v[12:15], v[118:121], v[114:117], v[12:15]
	ds_read_b128 v[114:117], v102 offset:4544
	s_waitcnt lgkmcnt(0)
	v_mfma_f32_16x16x32_bf16 v[32:35], v[110:113], v[114:117], v[32:35]
	v_mfma_f32_16x16x32_bf16 v[28:31], v[118:121], v[114:117], v[28:31]
	ds_read_b128 v[114:117], v102 offset:8896
	s_waitcnt lgkmcnt(0)
	v_mfma_f32_16x16x32_bf16 v[44:47], v[110:113], v[114:117], v[44:47]
	v_mfma_f32_16x16x32_bf16 v[40:43], v[118:121], v[114:117], v[40:43]
	ds_read_b128 v[114:117], v102 offset:13248
	s_waitcnt lgkmcnt(0)
	v_mfma_f32_16x16x32_bf16 v[8:11], v[110:113], v[114:117], v[8:11]
	v_mfma_f32_16x16x32_bf16 v[24:27], v[118:121], v[114:117], v[24:27]
	ds_read_u16 v71, v86 offset:27168
	ds_read_u16 v72, v86 offset:27712
	ds_read_u16 v73, v86 offset:28256
	ds_read_u16 v76, v86 offset:28800
	ds_read_u16 v77, v86 offset:29344
	ds_read_u16 v109, v86 offset:29888
	ds_read_u16 v110, v86 offset:30432
	ds_read_u16 v114, v86 offset:26624
	ds_read_u16 v118, v86 offset:26656
	ds_read_u16 v122, v86 offset:27200
	ds_read_u16 v119, v86 offset:27744
	ds_read_u16 v123, v86 offset:28288
	ds_read_u16 v120, v86 offset:28832
	ds_read_u16 v124, v86 offset:29376
	ds_read_u16 v121, v86 offset:29920
	ds_read_u16 v125, v86 offset:30464
	s_waitcnt lgkmcnt(9)
	v_perm_b32 v113, v110, v109, s13
	v_perm_b32 v112, v77, v76, s13
	v_perm_b32 v111, v73, v72, s13
	s_waitcnt lgkmcnt(8)
	v_perm_b32 v110, v71, v114, s13
	ds_read_b128 v[114:117], v104 offset:17408
	s_waitcnt lgkmcnt(1)
	v_perm_b32 v121, v125, v121, s13
	v_perm_b32 v120, v124, v120, s13
	v_perm_b32 v119, v123, v119, s13
	v_perm_b32 v118, v122, v118, s13
	s_waitcnt lgkmcnt(0)
	v_mfma_f32_16x16x32_bf16 v[16:19], v[110:113], v[114:117], v[16:19]
	v_mfma_f32_16x16x32_bf16 v[12:15], v[118:121], v[114:117], v[12:15]
	ds_read_b128 v[114:117], v104 offset:19712
	s_waitcnt lgkmcnt(0)
	v_mfma_f32_16x16x32_bf16 v[32:35], v[110:113], v[114:117], v[32:35]
	v_mfma_f32_16x16x32_bf16 v[28:31], v[118:121], v[114:117], v[28:31]
	ds_read_b128 v[114:117], v104 offset:22016
	s_waitcnt lgkmcnt(0)
; #define LAS __attribute__((address_space(3)))
; #define MFMA16(x, y, c) __builtin_amdgcn_mfma_f32_16x16x32_bf16((x), (y), (c), 0, 0, 0)
; __device__ __forceinline__ void gla_passC(LAS unsigned char* lds, int uidx, const bf16_t* PR, const bf16_t* SUB, const bf16_t* QT, const bf16_t* AM, const float* gn  ,
;                                           bf16_t* Y, int tid, int wid, int lane) {
;     ...
;         for (int it = 0; it < 4; ++it) { const bf16x8 y = *(const LAS bf16x8*)(As + (16 * it + r) * 72 + 32 * ks + 8 * q);
; #pragma unroll
;             for (int a = 0; a < 2; ++a) acc[a][it] = MFMA16(x[a], y, acc[a][it]); } }
;     __syncthreads();
; #pragma unroll
;     for (int a = 0; a < 2; ++a)
; #pragma unroll
;         for (int it = 0; it < 4; ++it) *(LAS f32x4*)(Of + (16 * it + r) * 260 + 32 * wid + 16 * a + 4 * q) = acc[a][it];
;     __syncthreads();
;     { const int i = tid >> 3, seg = tid & 7; f32x4 o[8]; float ss = 0.f;
; #pragma unroll
;       for (int j = 0; j < 8; ++j) { o[j] = *(const LAS f32x4*)(Of + i * 260 + seg * 32 + 4 * j); ss += (o[j].x * o[j].x + o[j].y * o[j].y) + (o[j].z * o[j].z + o[j].w * o[j].w); }
;       ss += __shfl_xor(ss, 1); ss += __shfl_xor(ss, 2); ss += __shfl_xor(ss, 4);
	v_mfma_f32_16x16x32_bf16 v[44:47], v[110:113], v[114:117], v[44:47]
	v_mfma_f32_16x16x32_bf16 v[40:43], v[118:121], v[114:117], v[40:43]
	ds_read_b128 v[114:117], v104 offset:24320
	s_waitcnt lgkmcnt(0)
	v_mfma_f32_16x16x32_bf16 v[8:11], v[110:113], v[114:117], v[8:11]
	v_mfma_f32_16x16x32_bf16 v[24:27], v[118:121], v[114:117], v[24:27]
	ds_read_u16 v71, v86 offset:44032
	ds_read_u16 v72, v86 offset:44576
	ds_read_u16 v73, v86 offset:45120
	ds_read_u16 v76, v86 offset:45664
	ds_read_u16 v77, v86 offset:46208
	ds_read_u16 v109, v86 offset:46752
	ds_read_u16 v110, v86 offset:47296
	ds_read_u16 v111, v86 offset:47840
	ds_read_u16 v118, v86 offset:44064
	ds_read_u16 v122, v86 offset:44608
	ds_read_u16 v119, v86 offset:45152
	ds_read_u16 v123, v86 offset:45696
	ds_read_u16 v120, v86 offset:46240
	ds_read_u16 v124, v86 offset:46784
	ds_read_u16 v121, v86 offset:47328
	ds_read_u16 v125, v86 offset:47872
	s_waitcnt lgkmcnt(8)
	v_perm_b32 v113, v111, v110, s13
	v_perm_b32 v112, v109, v77, s13
	v_perm_b32 v111, v76, v73, s13
	v_perm_b32 v110, v72, v71, s13
	ds_read_b128 v[114:117], v104 offset:17472
	s_waitcnt lgkmcnt(1)
	v_perm_b32 v121, v125, v121, s13
	v_perm_b32 v120, v124, v120, s13
	v_perm_b32 v119, v123, v119, s13
	v_perm_b32 v118, v122, v118, s13
	s_waitcnt lgkmcnt(0)
	v_mfma_f32_16x16x32_bf16 v[16:19], v[110:113], v[114:117], v[16:19]
	v_mfma_f32_16x16x32_bf16 v[12:15], v[118:121], v[114:117], v[12:15]
	ds_read_b128 v[114:117], v104 offset:19776
	s_waitcnt lgkmcnt(0)
	v_mfma_f32_16x16x32_bf16 v[32:35], v[110:113], v[114:117], v[32:35]
	v_mfma_f32_16x16x32_bf16 v[28:31], v[118:121], v[114:117], v[28:31]
	ds_read_b128 v[114:117], v104 offset:22080
	s_waitcnt lgkmcnt(0)
	v_mfma_f32_16x16x32_bf16 v[44:47], v[110:113], v[114:117], v[44:47]
	v_mfma_f32_16x16x32_bf16 v[40:43], v[118:121], v[114:117], v[40:43]
	ds_read_b128 v[114:117], v104 offset:24384
	s_waitcnt lgkmcnt(0)
	s_barrier
	v_mfma_f32_16x16x32_bf16 v[8:11], v[110:113], v[114:117], v[8:11]
	v_mfma_f32_16x16x32_bf16 v[24:27], v[118:121], v[114:117], v[24:27]
	ds_write_b128 v105, v[16:19] offset:61440
	ds_write_b128 v106, v[32:35] offset:61440
	ds_write_b128 v107, v[44:47] offset:61440
	s_nop 3
	ds_write_b128 v108, v[8:11] offset:61440
	ds_write_b128 v105, v[12:15] offset:61504
	ds_write_b128 v106, v[28:31] offset:61504
	ds_write_b128 v107, v[40:43] offset:61504
	ds_write_b128 v108, v[24:27] offset:61504
	s_waitcnt lgkmcnt(0)
	s_barrier
	ds_read_b128 v[44:47], v88 offset:61440
	ds_read_b128 v[40:43], v88 offset:61456
	ds_read_b128 v[32:35], v88 offset:61472
	ds_read_b128 v[28:31], v88 offset:61488
	ds_read_b128 v[24:27], v88 offset:61504
	ds_read_b128 v[16:19], v88 offset:61520
	s_waitcnt lgkmcnt(5)
	v_mov_b32_e32 v10, v45
	s_waitcnt lgkmcnt(4)
	v_mov_b32_e32 v11, v41
	v_mov_b32_e32 v8, v44
	v_mov_b32_e32 v9, v40
	v_pk_mul_f32 v[10:11], v[10:11], v[10:11]
	v_mov_b32_e32 v12, v47
	v_mov_b32_e32 v13, v43
	v_pk_fma_f32 v[8:9], v[8:9], v[8:9], v[10:11]
	v_mov_b32_e32 v10, v46
	v_mov_b32_e32 v11, v42
	v_pk_mul_f32 v[12:13], v[12:13], v[12:13]
	v_lshlrev_b32_e32 v118, 16, v36
	v_pk_fma_f32 v[10:11], v[10:11], v[10:11], v[12:13]
	s_waitcnt lgkmcnt(3)
	v_pk_mul_f32 v[12:13], v[32:33], v[32:33]
	v_pk_add_f32 v[8:9], v[8:9], v[10:11]
	v_pk_mul_f32 v[10:11], v[34:35], v[34:35]
	v_pk_add_f32 v[8:9], v[8:9], v[8:9] op_sel:[0,1] op_sel_hi:[1,0]
	v_pk_mov_b32 v[14:15], v[12:13], v[10:11] op_sel:[1,0]
	v_mov_b32_e32 v13, v11
	v_pk_add_f32 v[10:11], v[14:15], v[12:13]
	s_waitcnt lgkmcnt(1)
	v_mul_f32_e32 v12, v24, v24
	v_mul_f32_e32 v13, v25, v25
	v_pk_add_f32 v[10:11], v[10:11], v[10:11] op_sel:[0,1] op_sel_hi:[1,0]
	v_mov_b32_e32 v9, v12
	v_mov_b32_e32 v11, v13
	v_pk_add_f32 v[8:9], v[8:9], v[10:11]
	v_mul_f32_e32 v10, v29, v29
	v_mul_f32_e32 v12, v31, v31
	v_mul_f32_e32 v14, v26, v26
	v_mul_f32_e32 v15, v27, v27
	v_pk_fma_f32 v[10:11], v[28:29], v[28:29], v[10:11] op_sel_hi:[1,1,0]
	v_pk_fma_f32 v[12:13], v[30:31], v[30:31], v[12:13] op_sel_hi:[1,1,0]
	v_mov_b32_e32 v11, v14
	v_mov_b32_e32 v13, v15
	v_pk_add_f32 v[10:11], v[10:11], v[12:13]
	s_nop 0
	v_pk_add_f32 v[72:73], v[8:9], v[10:11]
	s_waitcnt lgkmcnt(0)
	v_pk_mul_f32 v[8:9], v[18:19], v[18:19]
	v_pk_mul_f32 v[10:11], v[16:17], v[16:17]
	v_pk_add_f32 v[72:73], v[72:73], v[72:73] op_sel:[0,1] op_sel_hi:[1,0]
	v_pk_mov_b32 v[12:13], v[10:11], v[8:9] op_sel:[1,0]
	v_mov_b32_e32 v11, v9
	v_pk_add_f32 v[76:77], v[12:13], v[10:11]
	ds_read_b128 v[12:15], v88 offset:61536
	ds_read_b128 v[8:11], v88 offset:61552
	v_pk_add_f32 v[76:77], v[76:77], v[76:77] op_sel:[0,1] op_sel_hi:[1,0]
	s_waitcnt lgkmcnt(0)
	v_mul_f32_e32 v71, v8, v8
	v_mul_f32_e32 v109, v9, v9
	v_mov_b32_e32 v73, v71
	v_mov_b32_e32 v77, v109
	v_pk_add_f32 v[72:73], v[72:73], v[76:77]
	v_mul_f32_e32 v76, v13, v13
	v_mul_f32_e32 v110, v10, v10
	v_pk_fma_f32 v[76:77], v[12:13], v[12:13], v[76:77] op_sel_hi:[1,1,0]
	v_mul_f32_e32 v112, v11, v11
	v_mov_b32_e32 v77, v110
	v_mul_f32_e32 v110, v15, v15
	v_pk_fma_f32 v[110:111], v[14:15], v[14:15], v[110:111] op_sel_hi:[1,1,0]
	s_nop 0
	v_mov_b32_e32 v111, v112
	v_pk_add_f32 v[76:77], v[76:77], v[110:111]
	s_nop 0
	v_pk_add_f32 v[72:73], v[72:73], v[76:77]
	v_lshl_add_u64 v[76:77], v[74:75], 0, v[168:169]
	v_add_f32_e32 v71, v72, v73
	ds_bpermute_b32 v72, v89, v71
	v_lshl_add_u64 v[74:75], v[76:77], 0, s[22:23]
	s_waitcnt lgkmcnt(0)
	v_add_f32_e32 v71, v71, v72
	ds_bpermute_b32 v72, v90, v71
	s_waitcnt lgkmcnt(0)
	v_add_f32_e32 v71, v71, v72
	ds_bpermute_b32 v72, v91, v71
	s_waitcnt lgkmcnt(0)
; __device__ __forceinline__ unsigned cvt_pk_bf16(float lo, float hi) { unsigned r; asm volatile("v_cvt_pk_bf16_f32 %0, %1, %2" : "=v"(r) : "v"(lo), "v"(hi)); return r; }
; #define LAS __attribute__((address_space(3)))
; __device__ __forceinline__ float bf_lo(unsigned w) { return __uint_as_float(w << 16); }
; __device__ __forceinline__ float bf_hi(unsigned w) { return __uint_as_float(w & 0xffff0000u); }
; __device__ __forceinline__ float silu_f(float x) { return x * __builtin_amdgcn_rcpf(1.f + __expf(-x)); }
; __device__ __forceinline__ void gla_passC(LAS unsigned char* lds, int uidx, const bf16_t* PR, const bf16_t* SUB, const bf16_t* QT, const bf16_t* AM, const float* gn  ,
;                                           bf16_t* Y, int tid, int wid, int lane) {
;     ...
;     { const int i = tid >> 3, seg = tid & 7; f32x4 o[8]; float ss = 0.f;
; #pragma unroll
;       for (int j = 0; j < 8; ++j) { o[j] = *(const LAS f32x4*)(Of + i * 260 + seg * 32 + 4 * j); ss += (o[j].x * o[j].x + o[j].y * o[j].y) + (o[j].z * o[j].z + o[j].w * o[j].w); }
;       ss += __shfl_xor(ss, 1); ss += __shfl_xor(ss, 2); ss += __shfl_xor(ss, 4);
;       const float rstd = rsqrtf(ss * (1.f / DV) + EPS);
;       const bf16_t* gp = PR + (size_t)(tok0 + i) * PRW + 3072 + h * DV + seg * 32; const float* gnp = gn + h * DV + seg * 32; bf16_t* yp = Y + (size_t)(tok0 + i) * DM + 1024 + h * DV + seg * 32;
; #pragma unroll
;       for (int j = 0; j < 4; ++j) { const u32x4 g = ogr[j]; const f32x4 n0 = *(const f32x4*)(gnp + 8 * j), n1 = *(const f32x4*)(gnp + 8 * j + 4); const f32x4 a0 = o[2 * j], a1 = o[2 * j + 1]; u32x4 w;
;           w.x = cvt_pk_bf16(a0.x * rstd * n0.x * silu_f(bf_lo(g.x)), a0.y * rstd * n0.y * silu_f(bf_hi(g.x)));
;           w.y = cvt_pk_bf16(a0.z * rstd * n0.z * silu_f(bf_lo(g.y)), a0.w * rstd * n0.w * silu_f(bf_hi(g.y)));
;           w.z = cvt_pk_bf16(a1.x * rstd * n1.x * silu_f(bf_lo(g.z)), a1.y * rstd * n1.y * silu_f(bf_hi(g.z)));
;           w.w = cvt_pk_bf16(a1.z * rstd * n1.z * silu_f(bf_lo(g.w)), a1.w * rstd * n1.w * silu_f(bf_hi(g.w)));
;           *(u32x4*)(yp + 8 * j) = w; } }
	v_add_f32_e32 v71, v71, v72
	v_fmamk_f32 v71, v71, 0x3b800000, v212
	v_cmp_gt_f32_e32 vcc, s14, v71
	v_mul_f32_e32 v72, 0x4b800000, v71
	s_nop 0
	v_cndmask_b32_e32 v71, v71, v72, vcc
	v_rsq_f32_e32 v71, v71
	s_nop 0
	v_mul_f32_e32 v72, 0x45800000, v71
	v_cndmask_b32_e32 v71, v71, v72, vcc
	v_lshl_add_u64 v[72:73], v[66:67], 0, s[10:11]
	global_load_dwordx4 v[110:113], v[72:73], off offset:16
	global_load_dwordx4 v[114:117], v[72:73], off
	v_mul_f32_e32 v119, v44, v71
	v_mul_f32_e32 v44, 0xbfb8aa3b, v118
	v_exp_f32_e32 v44, v44
	v_mul_f32_e32 v45, v45, v71
	v_mul_f32_e32 v41, v41, v71
	v_mul_f32_e32 v33, v33, v71
	v_add_f32_e32 v44, 1.0, v44
	v_rcp_f32_e32 v120, v44
	v_and_b32_e32 v44, 0xffff0000, v36
	v_mul_f32_e32 v36, 0xbfb8aa3b, v44
	v_exp_f32_e32 v36, v36
	v_mul_f32_e32 v29, v29, v71
	v_mul_f32_e32 v25, v25, v71
	v_mul_f32_e32 v17, v17, v71
	v_add_f32_e32 v36, 1.0, v36
	v_mul_f32_e32 v13, v13, v71
	v_mul_f32_e32 v9, v9, v71
	s_waitcnt vmcnt(0)
	v_mov_b32_e32 v121, v114
	v_rcp_f32_e32 v114, v36
	v_pk_mul_f32 v[118:119], v[120:121], v[118:119]
	v_pk_mul_f32 v[44:45], v[114:115], v[44:45]
	s_nop 0
	v_mul_f32_e32 v36, v44, v45
	v_lshlrev_b32_e32 v44, 16, v37
	v_mul_f32_e32 v45, v46, v71
	v_mul_f32_e32 v46, 0xbfb8aa3b, v44
	v_exp_f32_e32 v46, v46
	v_mov_b32_e32 v115, v116
	v_mul_f32_e32 v109, v118, v119
	v_cvt_pk_bf16_f32 v36, v109, v36
	v_add_f32_e32 v46, 1.0, v46
	v_rcp_f32_e32 v114, v46
	s_nop 0
	v_pk_mul_f32 v[44:45], v[114:115], v[44:45]
	s_nop 0
	v_mul_f32_e32 v46, v44, v45
	v_and_b32_e32 v44, 0xffff0000, v37
	v_mul_f32_e32 v37, 0xbfb8aa3b, v44
	v_exp_f32_e32 v37, v37
	v_mul_f32_e32 v45, v47, v71
	v_mov_b32_e32 v47, v110
	v_add_f32_e32 v37, 1.0, v37
	v_rcp_f32_e32 v116, v37
	s_nop 0
	v_pk_mul_f32 v[44:45], v[116:117], v[44:45]
	s_nop 0
	v_mul_f32_e32 v37, v44, v45
	v_lshlrev_b32_e32 v44, 16, v38
	v_mul_f32_e32 v45, v40, v71
	v_mul_f32_e32 v40, 0xbfb8aa3b, v44
	v_exp_f32_e32 v40, v40
	v_cvt_pk_bf16_f32 v37, v46, v37
	s_nop 0
	v_add_f32_e32 v40, 1.0, v40
	v_rcp_f32_e32 v46, v40
	v_and_b32_e32 v40, 0xffff0000, v38
	v_mul_f32_e32 v38, 0xbfb8aa3b, v40
	v_exp_f32_e32 v38, v38
	v_pk_mul_f32 v[44:45], v[46:47], v[44:45]
	v_add_f32_e32 v38, 1.0, v38
	v_rcp_f32_e32 v110, v38
	v_mul_f32_e32 v44, v44, v45
	v_mov_b32_e32 v45, v112
	v_pk_mul_f32 v[40:41], v[110:111], v[40:41]
	s_nop 0
	v_mul_f32_e32 v38, v40, v41
	v_lshlrev_b32_e32 v40, 16, v39
	v_mul_f32_e32 v41, v42, v71
	v_mul_f32_e32 v42, 0xbfb8aa3b, v40
	v_exp_f32_e32 v42, v42
	v_cvt_pk_bf16_f32 v38, v44, v38
	s_nop 0
	v_add_f32_e32 v42, 1.0, v42
	v_rcp_f32_e32 v44, v42
	s_nop 0
	v_pk_mul_f32 v[40:41], v[44:45], v[40:41]
	s_nop 0
	v_mul_f32_e32 v42, v40, v41
	v_and_b32_e32 v40, 0xffff0000, v39
	v_mul_f32_e32 v39, 0xbfb8aa3b, v40
	v_exp_f32_e32 v39, v39
	v_mul_f32_e32 v41, v43, v71
	v_lshlrev_b32_e32 v44, 16, v20
	v_mul_f32_e32 v45, v32, v71
	v_add_f32_e32 v39, 1.0, v39
	v_rcp_f32_e32 v112, v39
	v_mul_f32_e32 v32, 0xbfb8aa3b, v44
	v_exp_f32_e32 v32, v32
	v_pk_mul_f32 v[40:41], v[112:113], v[40:41]
	s_nop 0
	v_mul_f32_e32 v39, v40, v41
	v_add_co_u32_e32 v40, vcc, s7, v76
	v_cvt_pk_bf16_f32 v39, v42, v39
	v_add_f32_e32 v32, 1.0, v32
	s_nop 0
	v_addc_co_u32_e32 v41, vcc, 0, v77, vcc
	global_store_dwordx4 v[40:41], v[36:39], off offset:2048
	global_load_dwordx4 v[36:39], v[72:73], off offset:48
	s_nop 0
	global_load_dwordx4 v[40:43], v[72:73], off offset:32
	v_rcp_f32_e32 v46, v32
	v_and_b32_e32 v32, 0xffff0000, v20
	v_mul_f32_e32 v20, 0xbfb8aa3b, v32
	v_exp_f32_e32 v20, v20
	s_waitcnt vmcnt(0)
	v_mov_b32_e32 v47, v40
	v_add_f32_e32 v20, 1.0, v20
	v_rcp_f32_e32 v40, v20
	v_pk_mul_f32 v[44:45], v[46:47], v[44:45]
	v_pk_mul_f32 v[32:33], v[40:41], v[32:33]
	s_nop 0
	v_mul_f32_e32 v20, v32, v33
	v_lshlrev_b32_e32 v32, 16, v21
	v_mul_f32_e32 v33, v34, v71
	v_mul_f32_e32 v34, 0xbfb8aa3b, v32
	v_exp_f32_e32 v34, v34
	v_mov_b32_e32 v41, v42
	v_mul_f32_e32 v44, v44, v45
	v_cvt_pk_bf16_f32 v20, v44, v20
	v_add_f32_e32 v34, 1.0, v34
	v_rcp_f32_e32 v40, v34
	s_nop 0
	v_pk_mul_f32 v[32:33], v[40:41], v[32:33]
	s_nop 0
	v_mul_f32_e32 v34, v32, v33
	v_and_b32_e32 v32, 0xffff0000, v21
	v_mul_f32_e32 v21, 0xbfb8aa3b, v32
	v_exp_f32_e32 v21, v21
	v_mul_f32_e32 v33, v35, v71
	v_mov_b32_e32 v35, v36
	v_add_f32_e32 v21, 1.0, v21
	v_rcp_f32_e32 v42, v21
	s_nop 0
	v_pk_mul_f32 v[32:33], v[42:43], v[32:33]
	s_nop 0
	v_mul_f32_e32 v21, v32, v33
	v_lshlrev_b32_e32 v32, 16, v22
	v_mul_f32_e32 v33, v28, v71
	v_mul_f32_e32 v28, 0xbfb8aa3b, v32
	v_exp_f32_e32 v28, v28
	v_cvt_pk_bf16_f32 v21, v34, v21
	s_nop 0
	v_add_f32_e32 v28, 1.0, v28
	v_rcp_f32_e32 v34, v28
	v_and_b32_e32 v28, 0xffff0000, v22
	v_mul_f32_e32 v22, 0xbfb8aa3b, v28
	v_exp_f32_e32 v22, v22
	v_pk_mul_f32 v[32:33], v[34:35], v[32:33]
	v_lshlrev_b32_e32 v34, 16, v4
	v_mul_f32_e32 v32, v32, v33
	v_add_f32_e32 v22, 1.0, v22
	v_rcp_f32_e32 v36, v22
	v_mov_b32_e32 v33, v38
	v_pk_mul_f32 v[28:29], v[36:37], v[28:29]
	s_nop 0
	v_mul_f32_e32 v22, v28, v29
	v_lshlrev_b32_e32 v28, 16, v23
	v_mul_f32_e32 v29, v30, v71
	v_mul_f32_e32 v30, 0xbfb8aa3b, v28
	v_exp_f32_e32 v30, v30
	v_cvt_pk_bf16_f32 v22, v32, v22
	s_nop 0
	v_add_f32_e32 v30, 1.0, v30
	v_rcp_f32_e32 v32, v30
	s_nop 0
	v_pk_mul_f32 v[28:29], v[32:33], v[28:29]
	s_nop 0
	v_mul_f32_e32 v30, v28, v29
	v_and_b32_e32 v28, 0xffff0000, v23
	v_mul_f32_e32 v23, 0xbfb8aa3b, v28
	v_exp_f32_e32 v23, v23
	v_mul_f32_e32 v29, v31, v71
	v_mul_f32_e32 v33, v24, v71
	v_mul_f32_e32 v24, 0xbfb8aa3b, v34
	v_add_f32_e32 v23, 1.0, v23
	v_rcp_f32_e32 v38, v23
	v_exp_f32_e32 v24, v24
	v_pk_mul_f32 v[28:29], v[38:39], v[28:29]
	s_nop 0
	v_mul_f32_e32 v23, v28, v29
	v_cvt_pk_bf16_f32 v23, v30, v23
	global_store_dwordx4 v[74:75], v[20:23], off offset:16
	global_load_dwordx4 v[20:23], v[72:73], off offset:80
	s_nop 0
	global_load_dwordx4 v[28:31], v[72:73], off offset:64
	v_add_f32_e32 v24, 1.0, v24
	v_rcp_f32_e32 v32, v24
	s_waitcnt vmcnt(0)
; __device__ __forceinline__ unsigned cvt_pk_bf16(float lo, float hi) { unsigned r; asm volatile("v_cvt_pk_bf16_f32 %0, %1, %2" : "=v"(r) : "v"(lo), "v"(hi)); return r; }
; __device__ __forceinline__ float bf_lo(unsigned w) { return __uint_as_float(w << 16); }
; __device__ __forceinline__ float bf_hi(unsigned w) { return __uint_as_float(w & 0xffff0000u); }
; __device__ __forceinline__ float silu_f(float x) { return x * __builtin_amdgcn_rcpf(1.f + __expf(-x)); }
; __device__ __forceinline__ void gla_passC(LAS unsigned char* lds, int uidx, const bf16_t* PR, const bf16_t* SUB, const bf16_t* QT, const bf16_t* AM, const float* gn  ,
;                                           bf16_t* Y, int tid, int wid, int lane) {
;     ...
;       for (int j = 0; j < 4; ++j) { const u32x4 g = ogr[j]; const f32x4 n0 = *(const f32x4*)(gnp + 8 * j), n1 = *(const f32x4*)(gnp + 8 * j + 4); const f32x4 a0 = o[2 * j], a1 = o[2 * j + 1]; u32x4 w;
;           w.x = cvt_pk_bf16(a0.x * rstd * n0.x * silu_f(bf_lo(g.x)), a0.y * rstd * n0.y * silu_f(bf_hi(g.x)));
;           w.y = cvt_pk_bf16(a0.z * rstd * n0.z * silu_f(bf_lo(g.y)), a0.w * rstd * n0.w * silu_f(bf_hi(g.y)));
;           w.z = cvt_pk_bf16(a1.x * rstd * n1.x * silu_f(bf_lo(g.z)), a1.y * rstd * n1.y * silu_f(bf_hi(g.z)));
;           w.w = cvt_pk_bf16(a1.z * rstd * n1.z * silu_f(bf_lo(g.w)), a1.w * rstd * n1.w * silu_f(bf_hi(g.w)));
;           *(u32x4*)(yp + 8 * j) = w; } }
;     __syncthreads();
	v_mov_b32_e32 v35, v28
	v_and_b32_e32 v28, 0xffff0000, v4
	v_mul_f32_e32 v4, 0xbfb8aa3b, v28
	v_exp_f32_e32 v4, v4
	v_pk_mul_f32 v[32:33], v[32:33], v[34:35]
	v_add_f32_e32 v4, 1.0, v4
	v_rcp_f32_e32 v24, v4
	v_mul_f32_e32 v32, v32, v33
	v_pk_mul_f32 v[24:25], v[24:25], v[28:29]
	v_lshlrev_b32_e32 v28, 16, v5
	v_mul_f32_e32 v4, v24, v25
	v_mul_f32_e32 v24, 0xbfb8aa3b, v28
	v_exp_f32_e32 v24, v24
	v_mov_b32_e32 v29, v30
	v_and_b32_e32 v30, 0xffff0000, v5
	v_mul_f32_e32 v5, 0xbfb8aa3b, v30
	v_add_f32_e32 v24, 1.0, v24
	v_rcp_f32_e32 v24, v24
	v_exp_f32_e32 v5, v5
	v_mul_f32_e32 v25, v26, v71
	v_cvt_pk_bf16_f32 v4, v32, v4
	v_pk_mul_f32 v[24:25], v[24:25], v[28:29]
	v_add_f32_e32 v5, 1.0, v5
	v_mul_f32_e32 v26, v24, v25
	v_rcp_f32_e32 v24, v5
	v_mul_f32_e32 v25, v27, v71
	v_mov_b32_e32 v27, v20
	v_and_b32_e32 v20, 0xffff0000, v6
	v_pk_mul_f32 v[24:25], v[24:25], v[30:31]
	s_nop 0
	v_mul_f32_e32 v5, v24, v25
	v_cvt_pk_bf16_f32 v5, v26, v5
	v_lshlrev_b32_e32 v26, 16, v6
	v_mul_f32_e32 v25, v16, v71
	v_mul_f32_e32 v16, 0xbfb8aa3b, v26
	v_mul_f32_e32 v6, 0xbfb8aa3b, v20
	v_exp_f32_e32 v16, v16
	v_exp_f32_e32 v6, v6
	v_add_f32_e32 v16, 1.0, v16
	v_add_f32_e32 v6, 1.0, v6
	v_rcp_f32_e32 v24, v16
	v_rcp_f32_e32 v16, v6
	v_pk_mul_f32 v[24:25], v[24:25], v[26:27]
	v_pk_mul_f32 v[16:17], v[16:17], v[20:21]
	v_lshlrev_b32_e32 v20, 16, v7
	v_mul_f32_e32 v6, v16, v17
	v_mul_f32_e32 v16, 0xbfb8aa3b, v20
	v_exp_f32_e32 v16, v16
	v_mov_b32_e32 v21, v22
	v_and_b32_e32 v22, 0xffff0000, v7
	v_mul_f32_e32 v7, 0xbfb8aa3b, v22
	v_add_f32_e32 v16, 1.0, v16
	v_rcp_f32_e32 v16, v16
	v_exp_f32_e32 v7, v7
	v_mul_f32_e32 v17, v18, v71
	v_mul_f32_e32 v24, v24, v25
	v_pk_mul_f32 v[16:17], v[16:17], v[20:21]
	v_add_f32_e32 v7, 1.0, v7
	v_mul_f32_e32 v18, v16, v17
	v_rcp_f32_e32 v16, v7
	v_mul_f32_e32 v17, v19, v71
	v_cvt_pk_bf16_f32 v6, v24, v6
	v_mul_f32_e32 v21, v12, v71
	v_pk_mul_f32 v[16:17], v[16:17], v[22:23]
	v_lshlrev_b32_e32 v22, 16, v0
	v_mul_f32_e32 v7, v16, v17
	v_cvt_pk_bf16_f32 v7, v18, v7
	global_store_dwordx4 v[74:75], v[4:7], off offset:32
	global_load_dwordx4 v[4:7], v[72:73], off offset:112
	s_nop 0
	global_load_dwordx4 v[16:19], v[72:73], off offset:96
	v_mul_f32_e32 v12, 0xbfb8aa3b, v22
	v_exp_f32_e32 v12, v12
	s_waitcnt vmcnt(0)
	v_mov_b32_e32 v23, v16
	v_and_b32_e32 v16, 0xffff0000, v0
	v_mul_f32_e32 v0, 0xbfb8aa3b, v16
	v_exp_f32_e32 v0, v0
	v_add_f32_e32 v12, 1.0, v12
	v_rcp_f32_e32 v20, v12
	v_add_f32_e32 v0, 1.0, v0
	v_rcp_f32_e32 v12, v0
	v_pk_mul_f32 v[20:21], v[20:21], v[22:23]
	v_pk_mul_f32 v[12:13], v[12:13], v[16:17]
	v_lshlrev_b32_e32 v16, 16, v1
	v_mul_f32_e32 v0, v12, v13
	v_mul_f32_e32 v12, 0xbfb8aa3b, v16
	v_exp_f32_e32 v12, v12
	v_mov_b32_e32 v17, v18
	v_and_b32_e32 v18, 0xffff0000, v1
	v_mul_f32_e32 v1, 0xbfb8aa3b, v18
	v_add_f32_e32 v12, 1.0, v12
	v_rcp_f32_e32 v12, v12
	v_exp_f32_e32 v1, v1
	v_mul_f32_e32 v13, v14, v71
	v_mul_f32_e32 v20, v20, v21
	v_pk_mul_f32 v[12:13], v[12:13], v[16:17]
	v_add_f32_e32 v1, 1.0, v1
	v_mul_f32_e32 v14, v12, v13
	v_rcp_f32_e32 v12, v1
	v_mul_f32_e32 v13, v15, v71
	v_cvt_pk_bf16_f32 v0, v20, v0
	v_mov_b32_e32 v15, v4
	v_pk_mul_f32 v[12:13], v[12:13], v[18:19]
	v_and_b32_e32 v4, 0xffff0000, v2
	v_mul_f32_e32 v1, v12, v13
	v_cvt_pk_bf16_f32 v1, v14, v1
	v_lshlrev_b32_e32 v14, 16, v2
	v_mul_f32_e32 v13, v8, v71
	v_mul_f32_e32 v8, 0xbfb8aa3b, v14
	v_mul_f32_e32 v2, 0xbfb8aa3b, v4
	v_exp_f32_e32 v8, v8
	v_exp_f32_e32 v2, v2
	v_add_f32_e32 v8, 1.0, v8
	v_add_f32_e32 v2, 1.0, v2
	v_rcp_f32_e32 v12, v8
	v_rcp_f32_e32 v8, v2
	v_pk_mul_f32 v[12:13], v[12:13], v[14:15]
	v_pk_mul_f32 v[4:5], v[8:9], v[4:5]
	v_lshlrev_b32_e32 v8, 16, v3
	v_mul_f32_e32 v2, v4, v5
	v_mul_f32_e32 v4, 0xbfb8aa3b, v8
	v_exp_f32_e32 v4, v4
	v_mov_b32_e32 v9, v6
	v_and_b32_e32 v6, 0xffff0000, v3
	v_mul_f32_e32 v3, 0xbfb8aa3b, v6
	v_add_f32_e32 v4, 1.0, v4
	v_rcp_f32_e32 v4, v4
	v_exp_f32_e32 v3, v3
	v_mul_f32_e32 v5, v10, v71
	v_mul_f32_e32 v12, v12, v13
	v_pk_mul_f32 v[4:5], v[4:5], v[8:9]
	v_add_f32_e32 v3, 1.0, v3
	v_mul_f32_e32 v8, v4, v5
	v_rcp_f32_e32 v4, v3
	v_mul_f32_e32 v5, v11, v71
	v_cvt_pk_bf16_f32 v2, v12, v2
	v_pk_mul_f32 v[4:5], v[4:5], v[6:7]
	s_nop 0
	v_mul_f32_e32 v3, v4, v5
	v_cvt_pk_bf16_f32 v3, v8, v3
	global_store_dwordx4 v[74:75], v[0:3], off offset:48
	s_barrier
	s_cmpk_gt_i32 s6, 0x1ff
	s_cbranch_scc0 .LBB0_487
